# front pass-2 tile split 1/1/4/5 (one tile moved from batch 3 to batch 0)
# speedup vs baseline: 1.0123x; 1.0085x over previous
.LBB0_155:
	s_or_b64 exec, exec, s[0:1]
	s_mov_b32 s100, 1
	s_lshr_b32 s0, s83, 6
	s_and_b32 s1, s83, 63
	s_movk_i32 s4, 1
	s_movk_i32 s5, 512
	s_cmp_eq_u32 s0, 1
	s_cselect_b32 s4, 1, s4
	s_cselect_b32 s5, 576, s5
	s_cmp_eq_u32 s0, 2
	s_cselect_b32 s4, 4, s4
	s_cselect_b32 s5, 640, s5
	s_cmp_eq_u32 s0, 3
	s_cselect_b32 s4, 5, s4
	s_cselect_b32 s5, 896, s5
	s_mul_i32 s6, s1, s4
	s_add_i32 s8, s5, s6
	s_add_i32 s10, s8, s4
	s_cmp_eq_u32 s4, 0
	s_cbranch_scc1 .Lp0_second_done
	s_mul_i32 s3, s62, 0x2080
	s_mov_b32 s33, s3
	s_branch .LBB0_34
